# W_up transposes tiles 1498..2199 moved from P0 to the CUs idle in the last GEMM1 round (hand-written 128x128 transposes, b128 LDS)
# speedup vs baseline: 1.0048x; 1.0048x over previous
.LBB0_17:
	s_waitcnt lgkmcnt(0)
	v_writelane_b32 v237, s16, 28
	s_lshr_b32 s33, s10, 6
	s_cmp_lt_i32 s94, 1
	v_writelane_b32 v237, s17, 29
	v_writelane_b32 v237, s18, 30
	v_writelane_b32 v237, s19, 31
	v_writelane_b32 v237, s20, 32
	v_writelane_b32 v237, s21, 33
	v_writelane_b32 v237, s22, 34
	v_writelane_b32 v237, s23, 35
	v_writelane_b32 v237, s24, 36
	v_writelane_b32 v237, s25, 37
	v_writelane_b32 v237, s26, 38
	v_writelane_b32 v237, s27, 39
	v_writelane_b32 v237, s28, 40
	v_writelane_b32 v237, s29, 41
	v_writelane_b32 v237, s30, 42
	v_writelane_b32 v237, s31, 43
	s_load_dwordx16 s[36:51], s[0:1], 0x40
	s_load_dwordx16 s[12:27], s[0:1], 0x80
	s_cselect_b64 s[0:1], -1, 0
	s_cmp_gt_i32 s95, 0
	s_cselect_b64 s[2:3], -1, 0
	s_and_b64 s[68:69], s[0:1], s[2:3]
	s_waitcnt lgkmcnt(0)
	v_writelane_b32 v237, s12, 44
	s_andn2_b64 vcc, exec, s[68:69]
	v_and_b32_e32 v128, 63, v172
	v_writelane_b32 v237, s13, 45
	v_writelane_b32 v237, s14, 46
	v_writelane_b32 v237, s15, 47
	v_writelane_b32 v237, s16, 48
	v_writelane_b32 v237, s17, 49
	v_writelane_b32 v237, s18, 50
	v_writelane_b32 v237, s19, 51
	v_writelane_b32 v237, s20, 52
	v_writelane_b32 v237, s21, 53
	v_writelane_b32 v237, s22, 54
	v_writelane_b32 v237, s23, 55
	v_writelane_b32 v237, s24, 56
	v_writelane_b32 v237, s25, 57
	v_writelane_b32 v237, s26, 58
	v_writelane_b32 v237, s27, 59
	s_cbranch_vccnz .LBB0_147
	s_cmpk_eq_i32 s96, 0x100
	s_movk_i32 s0, 0x5da
	s_cselect_b32 s53, s0, 0xe10
	s_cmp_lt_i32 s76, s53
	v_mov_b32_e32 v35, v172
	s_cselect_b64 s[4:5], -1, 0
	s_and_b64 vcc, exec, s[4:5]
	v_ashrrev_i32_e32 v32, 5, v35
	v_lshlrev_b32_e32 v0, 2, v35
	s_cbranch_vccnz .LBB0_21
	v_ashrrev_i32_e32 v33, 5, v35
	v_and_b32_e32 v39, 0x7c, v0
	s_lshl_b32 s52, s76, 3
	s_cbranch_execz .LBB0_22
	v_mov_b32_e32 v31, 0
	v_mov_b32_e32 v30, v31
	v_mov_b32_e32 v29, v31
	v_mov_b32_e32 v28, v31
	v_mov_b32_e32 v27, v31
	v_mov_b32_e32 v26, v31
	v_mov_b32_e32 v25, v31
	v_mov_b32_e32 v24, v31
	v_mov_b32_e32 v23, v31
	v_mov_b32_e32 v22, v31
	v_mov_b32_e32 v21, v31
	v_mov_b32_e32 v20, v31
	v_mov_b32_e32 v19, v31
	v_mov_b32_e32 v18, v31
	v_mov_b32_e32 v17, v31
	v_mov_b32_e32 v16, v31
	v_mov_b32_e32 v15, v31
	v_mov_b32_e32 v14, v31
	v_mov_b32_e32 v13, v31
	v_mov_b32_e32 v12, v31
	v_mov_b32_e32 v11, v31
	v_mov_b32_e32 v10, v31
	v_mov_b32_e32 v9, v31
	v_mov_b32_e32 v8, v31
	v_mov_b32_e32 v7, v31
	v_mov_b32_e32 v6, v31
	v_mov_b32_e32 v5, v31
	v_mov_b32_e32 v4, v31
	v_mov_b32_e32 v3, v31
	v_mov_b32_e32 v2, v31
	v_mov_b32_e32 v1, v31
	v_mov_b32_e32 v0, v31
	v_mov_b32_e32 v32, v33
	s_andn2_b64 vcc, exec, s[4:5]
	s_cbranch_vccz .LBB0_72
	s_branch .LBB0_121

.LBB0_268:
	s_cmpk_lg_i32 s96, 0x100
	s_cbranch_scc1 .Ltup_skip
	s_cmpk_lt_u32 s76, 0x7b
	s_cbranch_scc1 .Ltup_skip
	s_cmpk_gt_u32 s76, 0xef
	s_cbranch_scc1 .Ltup_skip
	v_readlane_b32 s2, v237, 42
	v_readlane_b32 s3, v237, 43
	v_readlane_b32 s4, v237, 40
	v_readlane_b32 s5, v237, 41
	s_add_u32 s40, s92, 0x3000000
	s_addc_u32 s41, s93, 0
	v_and_b32_e32 v83, 31, v172
	v_lshrrev_b32_e32 v84, 5, v172
	v_mul_u32_u24_e32 v66, 0x58000, v84
	v_lshl_add_u32 v66, v83, 4, v66
	v_add_u32_e32 v67, 0xb000, v66
	v_add_u32_e32 v68, 0x16000, v66
	v_add_u32_e32 v69, 0x21000, v66
	v_add_u32_e32 v70, 0x2c000, v66
	v_add_u32_e32 v71, 0x37000, v66
	v_add_u32_e32 v72, 0x42000, v66
	v_add_u32_e32 v73, 0x4d000, v66
	v_lshlrev_b32_e32 v74, 5, v84
	v_and_b32_e32 v85, 15, v83
	v_xor_b32_e32 v85, v85, v84
	v_lshlrev_b32_e32 v85, 4, v85
	v_lshl_add_u32 v75, v83, 10, v85
	v_lshrrev_b32_e32 v83, 4, v172
	v_and_b32_e32 v84, 15, v172
	v_lshrrev_b32_e32 v85, 6, v172
	v_xor_b32_e32 v85, v85, v84
	v_lshlrev_b32_e32 v85, 4, v85
	v_lshl_add_u32 v76, v83, 8, v85
	v_xor_b32_e32 v77, 0x80, v76
	v_lshlrev_b32_e32 v84, 4, v84
	v_lshl_add_u32 v79, v83, 12, v84
	v_add_u32_e32 v80, 0x20000, v79
	v_add_u32_e32 v81, 0x40000, v79
	v_add_u32_e32 v82, 0x60000, v79
	s_add_i32 s9, s76, 0xffffff8f
	s_mul_i32 s12, s9, 0xba2f
	s_lshr_b32 s12, s12, 22
	s_mul_i32 s57, s12, 0x58
	s_sub_i32 s42, s9, s57
	s_mul_i32 s57, s12, 0x580000
	s_lshl_b32 s58, s42, 9
	s_add_i32 s57, s57, s58
	s_add_u32 s52, s2, s57
	s_addc_u32 s53, s3, 0
	s_lshl_b32 s58, s12, 9
	s_add_u32 s54, s4, s58
	s_addc_u32 s55, s5, 0
	s_cmp_gt_u32 s42, 43
	s_cselect_b32 s58, 0x80000, 0
	s_cselect_b32 s57, 44, 0
	s_sub_i32 s57, s42, s57
	s_lshl_b32 s57, s57, 20
	s_add_i32 s57, s57, s58
	s_lshl_b32 s58, s12, 8
	s_add_i32 s57, s57, s58
	s_add_u32 s60, s40, s57
	s_addc_u32 s61, s41, 0
	s_add_i32 s9, s9, 0x75
	s_nop 0
	global_load_dwordx4 v[206:209], v74, s[54:55] offset:0
	global_load_dwordx4 v[210:213], v74, s[54:55] offset:16
	global_load_dwordx4 v[174:177], v66, s[52:53]
	global_load_dwordx4 v[178:181], v67, s[52:53]
	global_load_dwordx4 v[182:185], v68, s[52:53]
	global_load_dwordx4 v[186:189], v69, s[52:53]
	global_load_dwordx4 v[190:193], v70, s[52:53]
	global_load_dwordx4 v[194:197], v71, s[52:53]
	global_load_dwordx4 v[198:201], v72, s[52:53]
	global_load_dwordx4 v[202:205], v73, s[52:53]
	s_mul_i32 s12, s9, 0xba2f
	s_lshr_b32 s12, s12, 22
	s_mul_i32 s57, s12, 0x58
	s_sub_i32 s42, s9, s57
	s_mul_i32 s57, s12, 0x580000
	s_lshl_b32 s58, s42, 9
	s_add_i32 s57, s57, s58
	s_add_u32 s62, s2, s57
	s_addc_u32 s63, s3, 0
	s_lshl_b32 s58, s12, 9
	s_add_u32 s64, s4, s58
	s_addc_u32 s65, s5, 0
	s_cmp_gt_u32 s42, 43
	s_cselect_b32 s58, 0x80000, 0
	s_cselect_b32 s57, 44, 0
	s_sub_i32 s57, s42, s57
	s_lshl_b32 s57, s57, 20
	s_add_i32 s57, s57, s58
	s_lshl_b32 s58, s12, 8
	s_add_i32 s57, s57, s58
	s_add_u32 s66, s40, s57
	s_addc_u32 s67, s41, 0
	s_add_i32 s9, s9, 0x75
	s_nop 0
	global_load_dwordx4 v[162:165], v74, s[64:65] offset:0
	global_load_dwordx4 v[166:169], v74, s[64:65] offset:16
	global_load_dwordx4 v[130:133], v66, s[62:63]
	global_load_dwordx4 v[134:137], v67, s[62:63]
	global_load_dwordx4 v[138:141], v68, s[62:63]
	global_load_dwordx4 v[142:145], v69, s[62:63]
	global_load_dwordx4 v[146:149], v70, s[62:63]
	global_load_dwordx4 v[150:153], v71, s[62:63]
	global_load_dwordx4 v[154:157], v72, s[62:63]
	global_load_dwordx4 v[158:161], v73, s[62:63]
	s_waitcnt vmcnt(10)
	v_mul_f32_e32 v174, v174, v206
	v_mul_f32_e32 v175, v175, v206
	v_mul_f32_e32 v176, v176, v206
	v_mul_f32_e32 v177, v177, v206
	v_mul_f32_e32 v178, v178, v207
	v_mul_f32_e32 v179, v179, v207
	v_mul_f32_e32 v180, v180, v207
	v_mul_f32_e32 v181, v181, v207
	v_mul_f32_e32 v182, v182, v208
	v_mul_f32_e32 v183, v183, v208
	v_mul_f32_e32 v184, v184, v208
	v_mul_f32_e32 v185, v185, v208
	v_mul_f32_e32 v186, v186, v209
	v_mul_f32_e32 v187, v187, v209
	v_mul_f32_e32 v188, v188, v209
	v_mul_f32_e32 v189, v189, v209
	v_mul_f32_e32 v190, v190, v210
	v_mul_f32_e32 v191, v191, v210
	v_mul_f32_e32 v192, v192, v210
	v_mul_f32_e32 v193, v193, v210
	v_mul_f32_e32 v194, v194, v211
	v_mul_f32_e32 v195, v195, v211
	v_mul_f32_e32 v196, v196, v211
	v_mul_f32_e32 v197, v197, v211
	v_mul_f32_e32 v198, v198, v212
	v_mul_f32_e32 v199, v199, v212
	v_mul_f32_e32 v200, v200, v212
	v_mul_f32_e32 v201, v201, v212
	v_mul_f32_e32 v202, v202, v213
	v_mul_f32_e32 v203, v203, v213
	v_mul_f32_e32 v204, v204, v213
	v_mul_f32_e32 v205, v205, v213
	v_cvt_pk_bf16_f32 v214, v174, v178
	v_cvt_pk_bf16_f32 v215, v182, v186
	v_cvt_pk_bf16_f32 v216, v190, v194
	v_cvt_pk_bf16_f32 v217, v198, v202
	v_cvt_pk_bf16_f32 v218, v175, v179
	v_cvt_pk_bf16_f32 v219, v183, v187
	v_cvt_pk_bf16_f32 v220, v191, v195
	v_cvt_pk_bf16_f32 v221, v199, v203
	v_cvt_pk_bf16_f32 v222, v176, v180
	v_cvt_pk_bf16_f32 v223, v184, v188
	v_cvt_pk_bf16_f32 v224, v192, v196
	v_cvt_pk_bf16_f32 v225, v200, v204
	v_cvt_pk_bf16_f32 v226, v177, v181
	v_cvt_pk_bf16_f32 v227, v185, v189
	v_cvt_pk_bf16_f32 v228, v193, v197
	v_cvt_pk_bf16_f32 v229, v201, v205
	ds_write_b128 v75, v[214:217] offset:0
	ds_write_b128 v75, v[218:221] offset:256
	ds_write_b128 v75, v[222:225] offset:512
	ds_write_b128 v75, v[226:229] offset:768
	s_mov_b64 s[68:69], s[60:61]
	s_mul_i32 s12, s9, 0xba2f
	s_lshr_b32 s12, s12, 22
	s_mul_i32 s57, s12, 0x58
	s_sub_i32 s42, s9, s57
	s_mul_i32 s57, s12, 0x580000
	s_lshl_b32 s58, s42, 9
	s_add_i32 s57, s57, s58
	s_add_u32 s52, s2, s57
	s_addc_u32 s53, s3, 0
	s_lshl_b32 s58, s12, 9
	s_add_u32 s54, s4, s58
	s_addc_u32 s55, s5, 0
	s_cmp_gt_u32 s42, 43
	s_cselect_b32 s58, 0x80000, 0
	s_cselect_b32 s57, 44, 0
	s_sub_i32 s57, s42, s57
	s_lshl_b32 s57, s57, 20
	s_add_i32 s57, s57, s58
	s_lshl_b32 s58, s12, 8
	s_add_i32 s57, s57, s58
	s_add_u32 s60, s40, s57
	s_addc_u32 s61, s41, 0
	s_add_i32 s9, s9, 0x75
	s_nop 0
	global_load_dwordx4 v[206:209], v74, s[54:55] offset:0
	global_load_dwordx4 v[210:213], v74, s[54:55] offset:16
	global_load_dwordx4 v[174:177], v66, s[52:53]
	global_load_dwordx4 v[178:181], v67, s[52:53]
	global_load_dwordx4 v[182:185], v68, s[52:53]
	global_load_dwordx4 v[186:189], v69, s[52:53]
	global_load_dwordx4 v[190:193], v70, s[52:53]
	global_load_dwordx4 v[194:197], v71, s[52:53]
	global_load_dwordx4 v[198:201], v72, s[52:53]
	global_load_dwordx4 v[202:205], v73, s[52:53]
	s_waitcnt lgkmcnt(0)
	s_barrier
	ds_read_b128 v[50:53], v76 offset:0
	ds_read_b128 v[54:57], v77 offset:8192
	ds_read_b128 v[58:61], v76 offset:16384
	ds_read_b128 v[62:65], v77 offset:24576
	s_waitcnt lgkmcnt(3)
	global_store_dwordx4 v79, v[50:53], s[68:69]
	s_waitcnt lgkmcnt(2)
	global_store_dwordx4 v80, v[54:57], s[68:69]
	s_waitcnt lgkmcnt(1)
	global_store_dwordx4 v81, v[58:61], s[68:69]
	s_waitcnt lgkmcnt(0)
	global_store_dwordx4 v82, v[62:65], s[68:69]
	s_waitcnt vmcnt(14)
	v_mul_f32_e32 v130, v130, v162
	v_mul_f32_e32 v131, v131, v162
	v_mul_f32_e32 v132, v132, v162
	v_mul_f32_e32 v133, v133, v162
	v_mul_f32_e32 v134, v134, v163
	v_mul_f32_e32 v135, v135, v163
	v_mul_f32_e32 v136, v136, v163
	v_mul_f32_e32 v137, v137, v163
	v_mul_f32_e32 v138, v138, v164
	v_mul_f32_e32 v139, v139, v164
	v_mul_f32_e32 v140, v140, v164
	v_mul_f32_e32 v141, v141, v164
	v_mul_f32_e32 v142, v142, v165
	v_mul_f32_e32 v143, v143, v165
	v_mul_f32_e32 v144, v144, v165
	v_mul_f32_e32 v145, v145, v165
	v_mul_f32_e32 v146, v146, v166
	v_mul_f32_e32 v147, v147, v166
	v_mul_f32_e32 v148, v148, v166
	v_mul_f32_e32 v149, v149, v166
	v_mul_f32_e32 v150, v150, v167
	v_mul_f32_e32 v151, v151, v167
	v_mul_f32_e32 v152, v152, v167
	v_mul_f32_e32 v153, v153, v167
	v_mul_f32_e32 v154, v154, v168
	v_mul_f32_e32 v155, v155, v168
	v_mul_f32_e32 v156, v156, v168
	v_mul_f32_e32 v157, v157, v168
	v_mul_f32_e32 v158, v158, v169
	v_mul_f32_e32 v159, v159, v169
	v_mul_f32_e32 v160, v160, v169
	v_mul_f32_e32 v161, v161, v169
	v_cvt_pk_bf16_f32 v214, v130, v134
	v_cvt_pk_bf16_f32 v215, v138, v142
	v_cvt_pk_bf16_f32 v216, v146, v150
	v_cvt_pk_bf16_f32 v217, v154, v158
	v_cvt_pk_bf16_f32 v218, v131, v135
	v_cvt_pk_bf16_f32 v219, v139, v143
	v_cvt_pk_bf16_f32 v220, v147, v151
	v_cvt_pk_bf16_f32 v221, v155, v159
	v_cvt_pk_bf16_f32 v222, v132, v136
	v_cvt_pk_bf16_f32 v223, v140, v144
	v_cvt_pk_bf16_f32 v224, v148, v152
	v_cvt_pk_bf16_f32 v225, v156, v160
	v_cvt_pk_bf16_f32 v226, v133, v137
	v_cvt_pk_bf16_f32 v227, v141, v145
	v_cvt_pk_bf16_f32 v228, v149, v153
	v_cvt_pk_bf16_f32 v229, v157, v161
	ds_write_b128 v75, v[214:217] offset:32768
	ds_write_b128 v75, v[218:221] offset:33024
	ds_write_b128 v75, v[222:225] offset:33280
	ds_write_b128 v75, v[226:229] offset:33536
	s_mov_b64 s[70:71], s[66:67]
	s_mul_i32 s12, s9, 0xba2f
	s_lshr_b32 s12, s12, 22
	s_mul_i32 s57, s12, 0x58
	s_sub_i32 s42, s9, s57
	s_mul_i32 s57, s12, 0x580000
	s_lshl_b32 s58, s42, 9
	s_add_i32 s57, s57, s58
	s_add_u32 s62, s2, s57
	s_addc_u32 s63, s3, 0
	s_lshl_b32 s58, s12, 9
	s_add_u32 s64, s4, s58
	s_addc_u32 s65, s5, 0
	s_cmp_gt_u32 s42, 43
	s_cselect_b32 s58, 0x80000, 0
	s_cselect_b32 s57, 44, 0
	s_sub_i32 s57, s42, s57
	s_lshl_b32 s57, s57, 20
	s_add_i32 s57, s57, s58
	s_lshl_b32 s58, s12, 8
	s_add_i32 s57, s57, s58
	s_add_u32 s66, s40, s57
	s_addc_u32 s67, s41, 0
	s_add_i32 s9, s9, 0x75
	s_nop 0
	global_load_dwordx4 v[162:165], v74, s[64:65] offset:0
	global_load_dwordx4 v[166:169], v74, s[64:65] offset:16
	global_load_dwordx4 v[130:133], v66, s[62:63]
	global_load_dwordx4 v[134:137], v67, s[62:63]
	global_load_dwordx4 v[138:141], v68, s[62:63]
	global_load_dwordx4 v[142:145], v69, s[62:63]
	global_load_dwordx4 v[146:149], v70, s[62:63]
	global_load_dwordx4 v[150:153], v71, s[62:63]
	global_load_dwordx4 v[154:157], v72, s[62:63]
	global_load_dwordx4 v[158:161], v73, s[62:63]
	s_waitcnt lgkmcnt(0)
	s_barrier
	ds_read_b128 v[102:105], v76 offset:32768
	ds_read_b128 v[106:109], v77 offset:40960
	ds_read_b128 v[110:113], v76 offset:49152
	ds_read_b128 v[114:117], v77 offset:57344
	s_waitcnt lgkmcnt(3)
	global_store_dwordx4 v79, v[102:105], s[70:71]
	s_waitcnt lgkmcnt(2)
	global_store_dwordx4 v80, v[106:109], s[70:71]
	s_waitcnt lgkmcnt(1)
	global_store_dwordx4 v81, v[110:113], s[70:71]
	s_waitcnt lgkmcnt(0)
	global_store_dwordx4 v82, v[114:117], s[70:71]
	s_waitcnt vmcnt(18)
	v_mul_f32_e32 v174, v174, v206
	v_mul_f32_e32 v175, v175, v206
	v_mul_f32_e32 v176, v176, v206
	v_mul_f32_e32 v177, v177, v206
	v_mul_f32_e32 v178, v178, v207
	v_mul_f32_e32 v179, v179, v207
	v_mul_f32_e32 v180, v180, v207
	v_mul_f32_e32 v181, v181, v207
	v_mul_f32_e32 v182, v182, v208
	v_mul_f32_e32 v183, v183, v208
	v_mul_f32_e32 v184, v184, v208
	v_mul_f32_e32 v185, v185, v208
	v_mul_f32_e32 v186, v186, v209
	v_mul_f32_e32 v187, v187, v209
	v_mul_f32_e32 v188, v188, v209
	v_mul_f32_e32 v189, v189, v209
	v_mul_f32_e32 v190, v190, v210
	v_mul_f32_e32 v191, v191, v210
	v_mul_f32_e32 v192, v192, v210
	v_mul_f32_e32 v193, v193, v210
	v_mul_f32_e32 v194, v194, v211
	v_mul_f32_e32 v195, v195, v211
	v_mul_f32_e32 v196, v196, v211
	v_mul_f32_e32 v197, v197, v211
	v_mul_f32_e32 v198, v198, v212
	v_mul_f32_e32 v199, v199, v212
	v_mul_f32_e32 v200, v200, v212
	v_mul_f32_e32 v201, v201, v212
	v_mul_f32_e32 v202, v202, v213
	v_mul_f32_e32 v203, v203, v213
	v_mul_f32_e32 v204, v204, v213
	v_mul_f32_e32 v205, v205, v213
	v_cvt_pk_bf16_f32 v214, v174, v178
	v_cvt_pk_bf16_f32 v215, v182, v186
	v_cvt_pk_bf16_f32 v216, v190, v194
	v_cvt_pk_bf16_f32 v217, v198, v202
	v_cvt_pk_bf16_f32 v218, v175, v179
	v_cvt_pk_bf16_f32 v219, v183, v187
	v_cvt_pk_bf16_f32 v220, v191, v195
	v_cvt_pk_bf16_f32 v221, v199, v203
	v_cvt_pk_bf16_f32 v222, v176, v180
	v_cvt_pk_bf16_f32 v223, v184, v188
	v_cvt_pk_bf16_f32 v224, v192, v196
	v_cvt_pk_bf16_f32 v225, v200, v204
	v_cvt_pk_bf16_f32 v226, v177, v181
	v_cvt_pk_bf16_f32 v227, v185, v189
	v_cvt_pk_bf16_f32 v228, v193, v197
	v_cvt_pk_bf16_f32 v229, v201, v205
	ds_write_b128 v75, v[214:217] offset:0
	ds_write_b128 v75, v[218:221] offset:256
	ds_write_b128 v75, v[222:225] offset:512
	ds_write_b128 v75, v[226:229] offset:768
	s_mov_b64 s[68:69], s[60:61]
	s_mul_i32 s12, s9, 0xba2f
	s_lshr_b32 s12, s12, 22
	s_mul_i32 s57, s12, 0x58
	s_sub_i32 s42, s9, s57
	s_mul_i32 s57, s12, 0x580000
	s_lshl_b32 s58, s42, 9
	s_add_i32 s57, s57, s58
	s_add_u32 s52, s2, s57
	s_addc_u32 s53, s3, 0
	s_lshl_b32 s58, s12, 9
	s_add_u32 s54, s4, s58
	s_addc_u32 s55, s5, 0
	s_cmp_gt_u32 s42, 43
	s_cselect_b32 s58, 0x80000, 0
	s_cselect_b32 s57, 44, 0
	s_sub_i32 s57, s42, s57
	s_lshl_b32 s57, s57, 20
	s_add_i32 s57, s57, s58
	s_lshl_b32 s58, s12, 8
	s_add_i32 s57, s57, s58
	s_add_u32 s60, s40, s57
	s_addc_u32 s61, s41, 0
	s_add_i32 s9, s9, 0x75
	s_nop 0
	global_load_dwordx4 v[206:209], v74, s[54:55] offset:0
	global_load_dwordx4 v[210:213], v74, s[54:55] offset:16
	global_load_dwordx4 v[174:177], v66, s[52:53]
	global_load_dwordx4 v[178:181], v67, s[52:53]
	global_load_dwordx4 v[182:185], v68, s[52:53]
	global_load_dwordx4 v[186:189], v69, s[52:53]
	global_load_dwordx4 v[190:193], v70, s[52:53]
	global_load_dwordx4 v[194:197], v71, s[52:53]
	global_load_dwordx4 v[198:201], v72, s[52:53]
	global_load_dwordx4 v[202:205], v73, s[52:53]
	s_waitcnt lgkmcnt(0)
	s_barrier
	ds_read_b128 v[50:53], v76 offset:0
	ds_read_b128 v[54:57], v77 offset:8192
	ds_read_b128 v[58:61], v76 offset:16384
	ds_read_b128 v[62:65], v77 offset:24576
	s_waitcnt lgkmcnt(3)
	global_store_dwordx4 v79, v[50:53], s[68:69]
	s_waitcnt lgkmcnt(2)
	global_store_dwordx4 v80, v[54:57], s[68:69]
	s_waitcnt lgkmcnt(1)
	global_store_dwordx4 v81, v[58:61], s[68:69]
	s_waitcnt lgkmcnt(0)
	global_store_dwordx4 v82, v[62:65], s[68:69]
	s_waitcnt vmcnt(18)
	v_mul_f32_e32 v130, v130, v162
	v_mul_f32_e32 v131, v131, v162
	v_mul_f32_e32 v132, v132, v162
	v_mul_f32_e32 v133, v133, v162
	v_mul_f32_e32 v134, v134, v163
	v_mul_f32_e32 v135, v135, v163
	v_mul_f32_e32 v136, v136, v163
	v_mul_f32_e32 v137, v137, v163
	v_mul_f32_e32 v138, v138, v164
	v_mul_f32_e32 v139, v139, v164
	v_mul_f32_e32 v140, v140, v164
	v_mul_f32_e32 v141, v141, v164
	v_mul_f32_e32 v142, v142, v165
	v_mul_f32_e32 v143, v143, v165
	v_mul_f32_e32 v144, v144, v165
	v_mul_f32_e32 v145, v145, v165
	v_mul_f32_e32 v146, v146, v166
	v_mul_f32_e32 v147, v147, v166
	v_mul_f32_e32 v148, v148, v166
	v_mul_f32_e32 v149, v149, v166
	v_mul_f32_e32 v150, v150, v167
	v_mul_f32_e32 v151, v151, v167
	v_mul_f32_e32 v152, v152, v167
	v_mul_f32_e32 v153, v153, v167
	v_mul_f32_e32 v154, v154, v168
	v_mul_f32_e32 v155, v155, v168
	v_mul_f32_e32 v156, v156, v168
	v_mul_f32_e32 v157, v157, v168
	v_mul_f32_e32 v158, v158, v169
	v_mul_f32_e32 v159, v159, v169
	v_mul_f32_e32 v160, v160, v169
	v_mul_f32_e32 v161, v161, v169
	v_cvt_pk_bf16_f32 v214, v130, v134
	v_cvt_pk_bf16_f32 v215, v138, v142
	v_cvt_pk_bf16_f32 v216, v146, v150
	v_cvt_pk_bf16_f32 v217, v154, v158
	v_cvt_pk_bf16_f32 v218, v131, v135
	v_cvt_pk_bf16_f32 v219, v139, v143
	v_cvt_pk_bf16_f32 v220, v147, v151
	v_cvt_pk_bf16_f32 v221, v155, v159
	v_cvt_pk_bf16_f32 v222, v132, v136
	v_cvt_pk_bf16_f32 v223, v140, v144
	v_cvt_pk_bf16_f32 v224, v148, v152
	v_cvt_pk_bf16_f32 v225, v156, v160
	v_cvt_pk_bf16_f32 v226, v133, v137
	v_cvt_pk_bf16_f32 v227, v141, v145
	v_cvt_pk_bf16_f32 v228, v149, v153
	v_cvt_pk_bf16_f32 v229, v157, v161
	ds_write_b128 v75, v[214:217] offset:32768
	ds_write_b128 v75, v[218:221] offset:33024
	ds_write_b128 v75, v[222:225] offset:33280
	ds_write_b128 v75, v[226:229] offset:33536
	s_mov_b64 s[70:71], s[66:67]
	s_mul_i32 s12, s9, 0xba2f
	s_lshr_b32 s12, s12, 22
	s_mul_i32 s57, s12, 0x58
	s_sub_i32 s42, s9, s57
	s_mul_i32 s57, s12, 0x580000
	s_lshl_b32 s58, s42, 9
	s_add_i32 s57, s57, s58
	s_add_u32 s62, s2, s57
	s_addc_u32 s63, s3, 0
	s_lshl_b32 s58, s12, 9
	s_add_u32 s64, s4, s58
	s_addc_u32 s65, s5, 0
	s_cmp_gt_u32 s42, 43
	s_cselect_b32 s58, 0x80000, 0
	s_cselect_b32 s57, 44, 0
	s_sub_i32 s57, s42, s57
	s_lshl_b32 s57, s57, 20
	s_add_i32 s57, s57, s58
	s_lshl_b32 s58, s12, 8
	s_add_i32 s57, s57, s58
	s_add_u32 s66, s40, s57
	s_addc_u32 s67, s41, 0
	s_add_i32 s9, s9, 0x75
	s_nop 0
	global_load_dwordx4 v[162:165], v74, s[64:65] offset:0
	global_load_dwordx4 v[166:169], v74, s[64:65] offset:16
	global_load_dwordx4 v[130:133], v66, s[62:63]
	global_load_dwordx4 v[134:137], v67, s[62:63]
	global_load_dwordx4 v[138:141], v68, s[62:63]
	global_load_dwordx4 v[142:145], v69, s[62:63]
	global_load_dwordx4 v[146:149], v70, s[62:63]
	global_load_dwordx4 v[150:153], v71, s[62:63]
	global_load_dwordx4 v[154:157], v72, s[62:63]
	global_load_dwordx4 v[158:161], v73, s[62:63]
	s_waitcnt lgkmcnt(0)
	s_barrier
	ds_read_b128 v[102:105], v76 offset:32768
	ds_read_b128 v[106:109], v77 offset:40960
	ds_read_b128 v[110:113], v76 offset:49152
	ds_read_b128 v[114:117], v77 offset:57344
	s_waitcnt lgkmcnt(3)
	global_store_dwordx4 v79, v[102:105], s[70:71]
	s_waitcnt lgkmcnt(2)
	global_store_dwordx4 v80, v[106:109], s[70:71]
	s_waitcnt lgkmcnt(1)
	global_store_dwordx4 v81, v[110:113], s[70:71]
	s_waitcnt lgkmcnt(0)
	global_store_dwordx4 v82, v[114:117], s[70:71]
	s_waitcnt vmcnt(18)
	v_mul_f32_e32 v174, v174, v206
	v_mul_f32_e32 v175, v175, v206
	v_mul_f32_e32 v176, v176, v206
	v_mul_f32_e32 v177, v177, v206
	v_mul_f32_e32 v178, v178, v207
	v_mul_f32_e32 v179, v179, v207
	v_mul_f32_e32 v180, v180, v207
	v_mul_f32_e32 v181, v181, v207
	v_mul_f32_e32 v182, v182, v208
	v_mul_f32_e32 v183, v183, v208
	v_mul_f32_e32 v184, v184, v208
	v_mul_f32_e32 v185, v185, v208
	v_mul_f32_e32 v186, v186, v209
	v_mul_f32_e32 v187, v187, v209
	v_mul_f32_e32 v188, v188, v209
	v_mul_f32_e32 v189, v189, v209
	v_mul_f32_e32 v190, v190, v210
	v_mul_f32_e32 v191, v191, v210
	v_mul_f32_e32 v192, v192, v210
	v_mul_f32_e32 v193, v193, v210
	v_mul_f32_e32 v194, v194, v211
	v_mul_f32_e32 v195, v195, v211
	v_mul_f32_e32 v196, v196, v211
	v_mul_f32_e32 v197, v197, v211
	v_mul_f32_e32 v198, v198, v212
	v_mul_f32_e32 v199, v199, v212
	v_mul_f32_e32 v200, v200, v212
	v_mul_f32_e32 v201, v201, v212
	v_mul_f32_e32 v202, v202, v213
	v_mul_f32_e32 v203, v203, v213
	v_mul_f32_e32 v204, v204, v213
	v_mul_f32_e32 v205, v205, v213
	v_cvt_pk_bf16_f32 v214, v174, v178
	v_cvt_pk_bf16_f32 v215, v182, v186
	v_cvt_pk_bf16_f32 v216, v190, v194
	v_cvt_pk_bf16_f32 v217, v198, v202
	v_cvt_pk_bf16_f32 v218, v175, v179
	v_cvt_pk_bf16_f32 v219, v183, v187
	v_cvt_pk_bf16_f32 v220, v191, v195
	v_cvt_pk_bf16_f32 v221, v199, v203
	v_cvt_pk_bf16_f32 v222, v176, v180
	v_cvt_pk_bf16_f32 v223, v184, v188
	v_cvt_pk_bf16_f32 v224, v192, v196
	v_cvt_pk_bf16_f32 v225, v200, v204
	v_cvt_pk_bf16_f32 v226, v177, v181
	v_cvt_pk_bf16_f32 v227, v185, v189
	v_cvt_pk_bf16_f32 v228, v193, v197
	v_cvt_pk_bf16_f32 v229, v201, v205
	ds_write_b128 v75, v[214:217] offset:0
	ds_write_b128 v75, v[218:221] offset:256
	ds_write_b128 v75, v[222:225] offset:512
	ds_write_b128 v75, v[226:229] offset:768
	s_mov_b64 s[68:69], s[60:61]
	s_waitcnt lgkmcnt(0)
	s_barrier
	ds_read_b128 v[50:53], v76 offset:0
	ds_read_b128 v[54:57], v77 offset:8192
	ds_read_b128 v[58:61], v76 offset:16384
	ds_read_b128 v[62:65], v77 offset:24576
	s_waitcnt lgkmcnt(3)
	global_store_dwordx4 v79, v[50:53], s[68:69]
	s_waitcnt lgkmcnt(2)
	global_store_dwordx4 v80, v[54:57], s[68:69]
	s_waitcnt lgkmcnt(1)
	global_store_dwordx4 v81, v[58:61], s[68:69]
	s_waitcnt lgkmcnt(0)
	global_store_dwordx4 v82, v[62:65], s[68:69]
	s_waitcnt vmcnt(8)
	v_mul_f32_e32 v130, v130, v162
	v_mul_f32_e32 v131, v131, v162
	v_mul_f32_e32 v132, v132, v162
	v_mul_f32_e32 v133, v133, v162
	v_mul_f32_e32 v134, v134, v163
	v_mul_f32_e32 v135, v135, v163
	v_mul_f32_e32 v136, v136, v163
	v_mul_f32_e32 v137, v137, v163
	v_mul_f32_e32 v138, v138, v164
	v_mul_f32_e32 v139, v139, v164
	v_mul_f32_e32 v140, v140, v164
	v_mul_f32_e32 v141, v141, v164
	v_mul_f32_e32 v142, v142, v165
	v_mul_f32_e32 v143, v143, v165
	v_mul_f32_e32 v144, v144, v165
	v_mul_f32_e32 v145, v145, v165
	v_mul_f32_e32 v146, v146, v166
	v_mul_f32_e32 v147, v147, v166
	v_mul_f32_e32 v148, v148, v166
	v_mul_f32_e32 v149, v149, v166
	v_mul_f32_e32 v150, v150, v167
	v_mul_f32_e32 v151, v151, v167
	v_mul_f32_e32 v152, v152, v167
	v_mul_f32_e32 v153, v153, v167
	v_mul_f32_e32 v154, v154, v168
	v_mul_f32_e32 v155, v155, v168
	v_mul_f32_e32 v156, v156, v168
	v_mul_f32_e32 v157, v157, v168
	v_mul_f32_e32 v158, v158, v169
	v_mul_f32_e32 v159, v159, v169
	v_mul_f32_e32 v160, v160, v169
	v_mul_f32_e32 v161, v161, v169
	v_cvt_pk_bf16_f32 v214, v130, v134
	v_cvt_pk_bf16_f32 v215, v138, v142
	v_cvt_pk_bf16_f32 v216, v146, v150
	v_cvt_pk_bf16_f32 v217, v154, v158
	v_cvt_pk_bf16_f32 v218, v131, v135
	v_cvt_pk_bf16_f32 v219, v139, v143
	v_cvt_pk_bf16_f32 v220, v147, v151
	v_cvt_pk_bf16_f32 v221, v155, v159
	v_cvt_pk_bf16_f32 v222, v132, v136
	v_cvt_pk_bf16_f32 v223, v140, v144
	v_cvt_pk_bf16_f32 v224, v148, v152
	v_cvt_pk_bf16_f32 v225, v156, v160
	v_cvt_pk_bf16_f32 v226, v133, v137
	v_cvt_pk_bf16_f32 v227, v141, v145
	v_cvt_pk_bf16_f32 v228, v149, v153
	v_cvt_pk_bf16_f32 v229, v157, v161
	ds_write_b128 v75, v[214:217] offset:32768
	ds_write_b128 v75, v[218:221] offset:33024
	ds_write_b128 v75, v[222:225] offset:33280
	ds_write_b128 v75, v[226:229] offset:33536
	s_mov_b64 s[70:71], s[66:67]
	s_waitcnt lgkmcnt(0)
	s_barrier
	ds_read_b128 v[102:105], v76 offset:32768
	ds_read_b128 v[106:109], v77 offset:40960
	ds_read_b128 v[110:113], v76 offset:49152
	ds_read_b128 v[114:117], v77 offset:57344
	s_waitcnt lgkmcnt(3)
	global_store_dwordx4 v79, v[102:105], s[70:71]
	s_waitcnt lgkmcnt(2)
	global_store_dwordx4 v80, v[106:109], s[70:71]
	s_waitcnt lgkmcnt(1)
	global_store_dwordx4 v81, v[110:113], s[70:71]
	s_waitcnt lgkmcnt(0)
	global_store_dwordx4 v82, v[114:117], s[70:71]
	s_waitcnt vmcnt(0)
	s_barrier
